# diff attention DMA via SGPR base + per-lane 32-bit offsets (no per-step VALU pointer updates or copies)
# speedup vs baseline: 1.0242x; 1.0062x over previous
; #define ATT_DMA2(ss) do { _Pragma("unroll") for (int hf = 0; hf < 2; ++hf) _Pragma("unroll") for (int j = 0; j < 4; ++j) if ((j * 8 + wave) * 64 < NKCH + NVCH) { \
;         __builtin_amdgcn_global_load_lds((const unsigned*)src[j], (LAS unsigned*)(lds + ((ss) * 2 + hf) * TILE + (j * 8 + wave) * 1024), 16, 0, 0); src[j] += step[j]; } } while (0)
; template <int DQK, int DV, int kpitch, int vpitch>
; DI void attn_map(LAS unsigned char* lds, const bf16x8 (&qf)[DQK / 16], const bf16* Kg, const bf16* Vg, f32x16 (&o)[DV / 32], float& lsum, int tid, int lane) {
;     ...
;     const bf16* src[4]; int step[4];
; #pragma unroll
;     for (int j = 0; j < 4; ++j) { int ci = (j * 8 + wave) * 64 + lane;
;         if (ci < NKCH) { const int row = ci / KCH, cc = ci % KCH; src[j] = Kg + (size_t)row * kpitch + (cc < KC ? cc : 0) * 8; step[j] = 64 * kpitch; }
;         else if (ci < NKCH + NVCH) { ci -= NKCH; const int row = ci / VCH, cc = ci % VCH; src[j] = Vg + (size_t)row * vpitch + (cc < VC ? cc : 0) * 8; step[j] = 64 * vpitch; }
;         else { src[j] = Kg; step[j] = 64 * kpitch; } }
;     ...
;     const int r = lane & 31, h = lane >> 5;
;     const int koff = r * KSTR + h * 16;
;     const int voff = KBUF + (4 * h + ((lane & 15) >> 2)) * VSTR + (((lane >> 4) & 1) * 16 + (lane & 3) * 4) * 2;
;     float l0 = 0.f, l1 = 0.f, l2 = 0.f, l3 = 0.f;
; #pragma unroll
;     for (int d = 0; d < DV / 32; ++d)
; #pragma unroll
;         for (int i = 0; i < 16; ++i) o[d][i] = 0.f;
;     asm volatile("" ::: "memory");
;     __builtin_amdgcn_s_barrier();
;     asm volatile("" ::: "memory");
;     ATT_DMA2(0);
.LBB0_1823:
	v_lshlrev_b32_e32 v196, 2, v200
	v_lshrrev_b32_e32 v2, 2, v208
	v_and_or_b32 v2, v2, 3, v196
	s_movk_i32 s10, 0x140
	v_and_b32_e32 v3, 16, v208
	v_lshlrev_b32_e32 v4, 2, v208
	v_lshlrev_b32_e32 v1, 4, v200
	v_mul_lo_u32 v2, v2, s10
	v_and_or_b32 v3, v4, 12, v3
	s_movk_i32 s10, 0x90
	v_mov_b32_e32 v169, 0
	v_mad_u32_u24 v197, v0, s10, v1
	s_lshl_b32 s22, s22, 10
	s_lshl_b32 s23, s23, 10
	s_lshl_b32 s24, s24, 10
	v_lshl_or_b32 v209, v3, 1, v2
	s_mov_b32 s26, 0
	v_mov_b32_e32 v171, 0
	v_mov_b32_e32 v168, 0
	v_mov_b32_e32 v170, 0
	v_mov_b32_e32 v0, 0
	v_mov_b32_e32 v1, v169
	v_mov_b32_e32 v2, v169
	v_mov_b32_e32 v3, v169
	v_mov_b32_e32 v4, v169
	v_mov_b32_e32 v5, v169
	v_mov_b32_e32 v6, v169
	v_mov_b32_e32 v7, v169
	v_mov_b32_e32 v8, v169
	v_mov_b32_e32 v9, v169
	v_mov_b32_e32 v10, v169
	v_mov_b32_e32 v11, v169
	v_mov_b32_e32 v12, v169
	v_mov_b32_e32 v13, v169
	v_mov_b32_e32 v14, v169
	v_mov_b32_e32 v15, v169
	v_mov_b32_e32 v16, 0
	v_mov_b32_e32 v17, v169
	v_mov_b32_e32 v18, v169
	v_mov_b32_e32 v19, v169
	v_mov_b32_e32 v20, v169
	v_mov_b32_e32 v21, v169
	v_mov_b32_e32 v22, v169
	v_mov_b32_e32 v23, v169
	v_mov_b32_e32 v24, v169
	v_mov_b32_e32 v25, v169
	v_mov_b32_e32 v26, v169
	v_mov_b32_e32 v27, v169
	v_mov_b32_e32 v28, v169
	v_mov_b32_e32 v29, v169
	v_mov_b32_e32 v30, v169
	v_mov_b32_e32 v31, v169
	v_mov_b32_e32 v32, 0
	v_mov_b32_e32 v33, v169
	v_mov_b32_e32 v34, v169
	v_mov_b32_e32 v35, v169
	v_mov_b32_e32 v36, v169
	v_mov_b32_e32 v37, v169
	v_mov_b32_e32 v38, v169
	v_mov_b32_e32 v39, v169
	v_mov_b32_e32 v40, v169
	v_mov_b32_e32 v41, v169
	v_mov_b32_e32 v42, v169
	v_mov_b32_e32 v43, v169
	v_mov_b32_e32 v44, v169
	v_mov_b32_e32 v45, v169
	v_mov_b32_e32 v46, v169
	v_mov_b32_e32 v47, v169
	v_mov_b32_e32 v48, 0
	v_mov_b32_e32 v49, v169
	v_mov_b32_e32 v50, v169
	v_mov_b32_e32 v51, v169
	v_mov_b32_e32 v52, v169
	v_mov_b32_e32 v53, v169
	v_mov_b32_e32 v54, v169
	v_mov_b32_e32 v55, v169
	v_mov_b32_e32 v56, v169
	v_mov_b32_e32 v57, v169
	v_mov_b32_e32 v58, v169
	v_mov_b32_e32 v59, v169
	v_mov_b32_e32 v60, v169
	v_mov_b32_e32 v61, v169
	v_mov_b32_e32 v62, v169
	v_mov_b32_e32 v63, v169
	s_waitcnt vmcnt(0)
	v_readfirstlane_b32 s86, v64
	v_readfirstlane_b32 s87, v65
	s_nop 0
	s_sub_u32 s86, s86, 0x100
	s_subb_u32 s87, s87, 0
	v_subrev_u32_e32 v128, s86, v64
	v_subrev_u32_e32 v130, s86, v66
	v_subrev_u32_e32 v132, s86, v68
	v_subrev_u32_e32 v134, s86, v70
	s_branch .LBB0_1825
.LBB0_1824:
	s_and_b32 s10, s26, 0x10000
	v_add_u32_e32 v176, s10, v197
	v_add_u32_e32 v201, s10, v209
	v_add_u32_e32 v201, 0x2400, v201
	s_and_b32 s27, s25, 0x10000
	s_cmp_eq_u32 s26, 0xf0000
	s_cselect_b64 s[44:45], -1, 0
	ds_read_b128 v[212:215], v176
	ds_read_b128 v[216:219], v176 offset:32
	ds_read_b128 v[220:223], v176 offset:64
	ds_read_b128 v[224:227], v176 offset:96
	ds_read_b128 v[172:175], v176 offset:4608
	ds_read_b128 v[178:181], v176 offset:4640
	s_waitcnt lgkmcnt(5)
	v_mfma_f32_32x32x16_bf16 v[64:79], v[212:215], v[136:139], 0
	ds_read_b128 v[212:215], v176 offset:4672
	s_or_b64 s[10:11], s[44:45], s[0:1]
	s_cbranch_scc1 .Ldiff1_dma_skip_0
	s_add_i32 m0, s27, s22
	s_nop 0
	global_load_lds_dwordx4 v128, s[86:87]
.Ldiff1_dma_skip_0:
	s_waitcnt lgkmcnt(5)
	v_mfma_f32_32x32x16_bf16 v[64:79], v[216:219], v[140:143], v[64:79]
	ds_read_b128 v[216:219], v176 offset:4704
	s_or_b64 s[10:11], s[44:45], s[38:39]
	s_cbranch_scc1 .Ldiff1_dma_skip_1
	s_add_i32 m0, s27, s23
	s_nop 0
	global_load_lds_dwordx4 v130, s[86:87]
.Ldiff1_dma_skip_1:
	s_waitcnt lgkmcnt(5)
	v_mfma_f32_32x32x16_bf16 v[64:79], v[220:223], v[144:147], v[64:79]
	ds_read_b128 v[220:223], v176 offset:32768
	s_or_b64 s[10:11], s[44:45], s[42:43]
	s_cbranch_scc1 .Ldiff1_dma_skip_2
	s_add_i32 m0, s27, s24
	s_nop 0
	global_load_lds_dwordx4 v132, s[86:87]
.Ldiff1_dma_skip_2:
	s_waitcnt lgkmcnt(5)
	v_mfma_f32_32x32x16_bf16 v[64:79], v[224:227], v[148:151], v[64:79]
	ds_read_b128 v[224:227], v176 offset:32800
	s_orn2_b64 s[10:11], s[44:45], s[68:69]
	s_cbranch_scc1 .Ldiff1_dma_skip_3
	s_add_i32 m0, s27, s13
	s_nop 0
	global_load_lds_dwordx4 v134, s[86:87]
.Ldiff1_dma_skip_3:
	s_add_u32 s86, s86, s82
	s_addc_u32 s87, s87, s83
	s_waitcnt lgkmcnt(5)
	v_mfma_f32_32x32x16_bf16 v[80:95], v[172:175], v[136:139], 0
	ds_read_b128 v[172:175], v176 offset:32832
	s_or_b64 s[10:11], s[44:45], s[0:1]
	s_cbranch_scc1 .Ldiff1_dma_skip_4
	s_add_i32 s10, s27, s22
	s_add_i32 m0, s10, 0x8000
	s_nop 0
	global_load_lds_dwordx4 v128, s[86:87]
.Ldiff1_dma_skip_4:
	s_waitcnt lgkmcnt(5)
	v_mfma_f32_32x32x16_bf16 v[80:95], v[178:181], v[140:143], v[80:95]
	ds_read_b128 v[178:181], v176 offset:32864
	s_or_b64 s[10:11], s[44:45], s[38:39]
	s_cbranch_scc1 .Ldiff1_dma_skip_5
	s_add_i32 s10, s27, s23
	s_add_i32 m0, s10, 0x8000
	s_nop 0
	global_load_lds_dwordx4 v130, s[86:87]
.Ldiff1_dma_skip_5:
	v_exp_f32_e32 v64, v64
	v_exp_f32_e32 v65, v65
	v_exp_f32_e32 v66, v66
	s_waitcnt lgkmcnt(5)
	v_mfma_f32_32x32x16_bf16 v[80:95], v[212:215], v[144:147], v[80:95]
	ds_read_b128 v[212:215], v176 offset:37376
	s_or_b64 s[10:11], s[44:45], s[42:43]
	s_cbranch_scc1 .Ldiff1_dma_skip_6
	s_add_i32 s10, s27, s24
	s_add_i32 m0, s10, 0x8000
	s_nop 0
	global_load_lds_dwordx4 v132, s[86:87]
.Ldiff1_dma_skip_6:
	v_exp_f32_e32 v67, v67
	v_exp_f32_e32 v68, v68
	v_exp_f32_e32 v69, v69
	s_waitcnt lgkmcnt(5)
	v_mfma_f32_32x32x16_bf16 v[80:95], v[216:219], v[148:151], v[80:95]
	ds_read_b128 v[216:219], v176 offset:37408
	ds_read_b64_tr_b16 v[112:113], v201
	ds_read_b64_tr_b16 v[114:115], v201 offset:2560
	s_orn2_b64 s[10:11], s[44:45], s[68:69]
	s_cbranch_scc1 .Ldiff1_dma_skip_7
	s_add_i32 s10, s27, s13
	s_add_i32 m0, s10, 0x8000
	s_nop 0
	global_load_lds_dwordx4 v134, s[86:87]
; #define LAS __attribute__((address_space(3)))
; #define MFMA32(a, b, c) __builtin_amdgcn_mfma_f32_32x32x16_bf16((a), (b), (c), 0, 0, 0)
; #define VTR_SET(lo, hi, c) do { _Pragma("unroll") for (int d = 0; d < ND; ++d) { \
;         VTR_ASM(lo[d], va, (32 * ((c) >> 1) + 16 * ((c) & 1)) * VSTR + d * 64); VTR_ASM(hi[d], va, (32 * ((c) >> 1) + 16 * ((c) & 1)) * VSTR + d * 64 + 8 * VSTR); } } while (0)
; #define PV_MMA(lo, hi, c) do { _Pragma("unroll") for (int d = 0; d < ND; ++d) { const bf16x8 vf = __builtin_shufflevector(lo[d], hi[d], 0, 1, 2, 3, 4, 5, 6, 7); o[d] = MFMA32(vf, pf[(c) >> 1][(c) & 1], o[d]); } } while (0)
; #define VTR_SET(lo, hi, base, c) do { _Pragma("unroll") for (int d = 0; d < ND; ++d) { \
;         VTR_ASM(lo[d], base, (32 * ((c) >> 1) + 16 * ((c) & 1)) * VSTR + d * 64); VTR_ASM(hi[d], base, (32 * ((c) >> 1) + 16 * ((c) & 1)) * VSTR + d * 64 + 8 * VSTR); } } while (0)
; #define PV_MMA(lo, hi, pf_) do { _Pragma("unroll") for (int d = 0; d < ND; ++d) { const bf16x8 vf = __builtin_shufflevector(lo[d], hi[d], 0, 1, 2, 3, 4, 5, 6, 7); o[d] = MFMA32(vf, pf_, o[d]); } } while (0)
; template <int DQK, int DV, int KSTR, int VSTR>
; DI void attn_step2(const LAS unsigned char* ta, const LAS unsigned char* tb, int koff, int voff, const bf16x8 (&qf)[DQK / 16], f32x16 (&o)[DV / 32], float& l0, float& l1, float& l2, float& l3) {
;     ...
;     for (int c = 0; c < 4; ++c) {
; #pragma unroll
;         for (int ks = (c * NKS) / 4; ks < ((c + 1) * NKS) / 4; ++ks) {
;             const bf16x8 k0 = *(const LAS bf16x8*)(tb + koff + ks * 32), k1 = *(const LAS bf16x8*)(tb + koff + 32 * KSTR + ks * 32);
;             sb[0] = MFMA32(k0, qf[ks], ks == 0 ? zero16 : sb[0]); sb[1] = MFMA32(k1, qf[ks], ks == 0 ? zero16 : sb[1]);
;         }
;         SM_CHUNK(sa, pfa[c], c);
;     }
;     vtr_wait<ND>(alo, ahi); VTR_SET(blo, bhi, va, 1); PV_MMA(alo, ahi, pfa[0]); SM_CHUNK(sb, pfb[0], 0);
;     vtr_wait<ND>(blo, bhi); VTR_SET(alo, ahi, va, 2); PV_MMA(blo, bhi, pfa[1]); SM_CHUNK(sb, pfb[1], 1);
;     vtr_wait<ND>(alo, ahi); VTR_SET(blo, bhi, va, 3); PV_MMA(alo, ahi, pfa[2]); SM_CHUNK(sb, pfb[2], 2);
;     vtr_wait<ND>(blo, bhi); VTR_SET(alo, ahi, vb, 0); PV_MMA(blo, bhi, pfa[3]); SM_CHUNK(sb, pfb[3], 3);
.Ldiff1_dma_skip_7:
	s_add_u32 s86, s86, s82
	s_addc_u32 s87, s87, s83
	v_exp_f32_e32 v70, v70
	v_exp_f32_e32 v71, v71
	v_exp_f32_e32 v72, v72
	s_waitcnt lgkmcnt(7)
	v_mfma_f32_32x32x16_bf16 v[96:111], v[220:223], v[136:139], 0
	ds_read_b128 v[220:223], v176 offset:37440
	ds_read_b64_tr_b16 v[116:117], v201 offset:64
	ds_read_b64_tr_b16 v[118:119], v201 offset:2624
	v_exp_f32_e32 v73, v73
	v_exp_f32_e32 v74, v74
	v_exp_f32_e32 v75, v75
	s_waitcnt lgkmcnt(9)
	v_mfma_f32_32x32x16_bf16 v[96:111], v[224:227], v[140:143], v[96:111]
	ds_read_b128 v[224:227], v176 offset:37472
	ds_read_b64_tr_b16 v[120:121], v201 offset:128
	ds_read_b64_tr_b16 v[122:123], v201 offset:2688
	v_exp_f32_e32 v76, v76
	v_exp_f32_e32 v77, v77
	v_exp_f32_e32 v78, v78
	s_waitcnt lgkmcnt(11)
	v_mfma_f32_32x32x16_bf16 v[96:111], v[172:175], v[144:147], v[96:111]
	ds_read_b64_tr_b16 v[124:125], v201 offset:192
	ds_read_b64_tr_b16 v[126:127], v201 offset:2752
	v_exp_f32_e32 v79, v79
	v_cvt_pk_bf16_f32 v152, v64, v65
	v_cvt_pk_bf16_f32 v153, v66, v67
	v_cvt_pk_bf16_f32 v154, v68, v69
	v_cvt_pk_bf16_f32 v155, v70, v71
	s_waitcnt lgkmcnt(12)
	v_mfma_f32_32x32x16_bf16 v[96:111], v[178:181], v[148:151], v[96:111]
	v_cvt_pk_bf16_f32 v156, v72, v73
	v_cvt_pk_bf16_f32 v157, v74, v75
	v_cvt_pk_bf16_f32 v158, v76, v77
	v_cvt_pk_bf16_f32 v159, v78, v79
	v_exp_f32_e32 v80, v80
	s_waitcnt lgkmcnt(8)
	v_mfma_f32_32x32x16_bf16 v[48:63], v[112:115], v[152:155], v[48:63]
	ds_read_b64_tr_b16 v[112:113], v201 offset:5120
	ds_read_b64_tr_b16 v[114:115], v201 offset:7680
	v_exp_f32_e32 v81, v81
	v_exp_f32_e32 v82, v82
	v_exp_f32_e32 v83, v83
	s_waitcnt lgkmcnt(7)
	v_mfma_f32_32x32x16_bf16 v[32:47], v[116:119], v[152:155], v[32:47]
	ds_read_b64_tr_b16 v[116:117], v201 offset:5184
	ds_read_b64_tr_b16 v[118:119], v201 offset:7744
	v_exp_f32_e32 v84, v84
	v_exp_f32_e32 v85, v85
	v_exp_f32_e32 v86, v86
	s_waitcnt lgkmcnt(6)
	v_mfma_f32_32x32x16_bf16 v[16:31], v[120:123], v[152:155], v[16:31]
	ds_read_b64_tr_b16 v[120:121], v201 offset:5248
	ds_read_b64_tr_b16 v[122:123], v201 offset:7808
	v_exp_f32_e32 v87, v87
	v_exp_f32_e32 v88, v88
	v_exp_f32_e32 v89, v89
	s_waitcnt lgkmcnt(6)
	v_mfma_f32_32x32x16_bf16 v[0:15], v[124:127], v[152:155], v[0:15]
	ds_read_b64_tr_b16 v[124:125], v201 offset:5312
	ds_read_b64_tr_b16 v[126:127], v201 offset:7872
	v_exp_f32_e32 v90, v90
	v_exp_f32_e32 v91, v91
	v_exp_f32_e32 v92, v92
	s_waitcnt lgkmcnt(6)
	v_mfma_f32_32x32x16_bf16 v[48:63], v[112:115], v[156:159], v[48:63]
	ds_read_b64_tr_b16 v[112:113], v201 offset:10240
	ds_read_b64_tr_b16 v[114:115], v201 offset:12800
	v_exp_f32_e32 v93, v93
	v_exp_f32_e32 v94, v94
	v_exp_f32_e32 v95, v95
	s_waitcnt lgkmcnt(6)
	v_mfma_f32_32x32x16_bf16 v[32:47], v[116:119], v[156:159], v[32:47]
	ds_read_b64_tr_b16 v[116:117], v201 offset:10304
	ds_read_b64_tr_b16 v[118:119], v201 offset:12864
	v_cvt_pk_bf16_f32 v160, v80, v81
	v_cvt_pk_bf16_f32 v161, v82, v83
	v_cvt_pk_bf16_f32 v162, v84, v85
	v_cvt_pk_bf16_f32 v163, v86, v87
	v_cvt_pk_bf16_f32 v164, v88, v89
	v_cvt_pk_bf16_f32 v165, v90, v91
	s_waitcnt lgkmcnt(6)
	v_mfma_f32_32x32x16_bf16 v[16:31], v[120:123], v[156:159], v[16:31]
	ds_read_b64_tr_b16 v[120:121], v201 offset:10368
	ds_read_b64_tr_b16 v[122:123], v201 offset:12928
	v_cvt_pk_bf16_f32 v166, v92, v93
	v_cvt_pk_bf16_f32 v167, v94, v95
	v_exp_f32_e32 v96, v96
	v_exp_f32_e32 v97, v97
	s_waitcnt lgkmcnt(6)
	v_mfma_f32_32x32x16_bf16 v[0:15], v[124:127], v[156:159], v[0:15]
	ds_read_b64_tr_b16 v[124:125], v201 offset:10432
	ds_read_b64_tr_b16 v[126:127], v201 offset:12992
	v_exp_f32_e32 v98, v98
	v_exp_f32_e32 v99, v99
	v_exp_f32_e32 v100, v100
	v_add_f32_e32 v168, v168, v64
	v_add_f32_e32 v169, v169, v65
	v_add_f32_e32 v170, v170, v66
	v_add_f32_e32 v171, v171, v67
	v_add_f32_e32 v168, v168, v68
	v_add_f32_e32 v169, v169, v69
	v_add_f32_e32 v170, v170, v70
	v_add_f32_e32 v171, v171, v71
	v_add_f32_e32 v168, v168, v72
	v_add_f32_e32 v169, v169, v73
	v_add_f32_e32 v170, v170, v74
	v_add_f32_e32 v171, v171, v75
	v_add_f32_e32 v168, v168, v76
	v_add_f32_e32 v169, v169, v77
	v_add_f32_e32 v170, v170, v78
	v_add_f32_e32 v171, v171, v79
	v_mfma_f32_32x32x16_bf16 v[64:79], v[212:215], v[136:139], 0
	v_exp_f32_e32 v101, v101
	v_exp_f32_e32 v102, v102
	v_exp_f32_e32 v103, v103
	v_mfma_f32_32x32x16_bf16 v[64:79], v[216:219], v[140:143], v[64:79]
	v_exp_f32_e32 v104, v104
	v_exp_f32_e32 v105, v105
	v_exp_f32_e32 v106, v106
	v_mfma_f32_32x32x16_bf16 v[64:79], v[220:223], v[144:147], v[64:79]
	v_exp_f32_e32 v107, v107
	v_exp_f32_e32 v108, v108
	v_exp_f32_e32 v109, v109
	v_mfma_f32_32x32x16_bf16 v[64:79], v[224:227], v[148:151], v[64:79]
	v_exp_f32_e32 v110, v110
	v_exp_f32_e32 v111, v111
	v_cvt_pk_bf16_f32 v152, v96, v97
	s_waitcnt lgkmcnt(6)
	v_mfma_f32_32x32x16_bf16 v[48:63], v[112:115], v[160:163], v[48:63]
	ds_read_b64_tr_b16 v[112:113], v201 offset:15360
	ds_read_b64_tr_b16 v[114:115], v201 offset:17920
	v_cvt_pk_bf16_f32 v153, v98, v99
	v_cvt_pk_bf16_f32 v154, v100, v101
	v_cvt_pk_bf16_f32 v155, v102, v103
	v_cvt_pk_bf16_f32 v156, v104, v105
	v_cvt_pk_bf16_f32 v157, v106, v107
	s_waitcnt lgkmcnt(6)
	v_mfma_f32_32x32x16_bf16 v[32:47], v[116:119], v[160:163], v[32:47]
	ds_read_b64_tr_b16 v[116:117], v201 offset:15424
	ds_read_b64_tr_b16 v[118:119], v201 offset:17984
	v_cvt_pk_bf16_f32 v158, v108, v109
	v_cvt_pk_bf16_f32 v159, v110, v111
	v_exp_f32_e32 v64, v64
	v_exp_f32_e32 v65, v65
	s_waitcnt lgkmcnt(6)
	v_mfma_f32_32x32x16_bf16 v[16:31], v[120:123], v[160:163], v[16:31]
	ds_read_b64_tr_b16 v[120:121], v201 offset:15488
	ds_read_b64_tr_b16 v[122:123], v201 offset:18048
	v_exp_f32_e32 v66, v66
	v_exp_f32_e32 v67, v67
	v_exp_f32_e32 v68, v68
	s_waitcnt lgkmcnt(6)
; #define LAS __attribute__((address_space(3)))
; #define VTR_SET(lo, hi, c) do { _Pragma("unroll") for (int d = 0; d < ND; ++d) { \
;         VTR_ASM(lo[d], va, (32 * ((c) >> 1) + 16 * ((c) & 1)) * VSTR + d * 64); VTR_ASM(hi[d], va, (32 * ((c) >> 1) + 16 * ((c) & 1)) * VSTR + d * 64 + 8 * VSTR); } } while (0)
; #define PV_MMA(lo, hi, c) do { _Pragma("unroll") for (int d = 0; d < ND; ++d) { const bf16x8 vf = __builtin_shufflevector(lo[d], hi[d], 0, 1, 2, 3, 4, 5, 6, 7); o[d] = MFMA32(vf, pf[(c) >> 1][(c) & 1], o[d]); } } while (0)
; #define VTR_SET(lo, hi, base, c) do { _Pragma("unroll") for (int d = 0; d < ND; ++d) { \
;         VTR_ASM(lo[d], base, (32 * ((c) >> 1) + 16 * ((c) & 1)) * VSTR + d * 64); VTR_ASM(hi[d], base, (32 * ((c) >> 1) + 16 * ((c) & 1)) * VSTR + d * 64 + 8 * VSTR); } } while (0)
; template <int DQK, int DV, int KSTR, int VSTR>
; DI void attn_step2(const LAS unsigned char* ta, const LAS unsigned char* tb, int koff, int voff, const bf16x8 (&qf)[DQK / 16], f32x16 (&o)[DV / 32], float& l0, float& l1, float& l2, float& l3) {
;     ...
;     vtr_wait<ND>(blo, bhi); VTR_SET(alo, ahi, va, 2); PV_MMA(blo, bhi, pfa[1]); SM_CHUNK(sb, pfb[1], 1);
;     vtr_wait<ND>(alo, ahi); VTR_SET(blo, bhi, va, 3); PV_MMA(alo, ahi, pfa[2]); SM_CHUNK(sb, pfb[2], 2);
;     vtr_wait<ND>(blo, bhi); VTR_SET(alo, ahi, vb, 0); PV_MMA(blo, bhi, pfa[3]); SM_CHUNK(sb, pfb[3], 3);
;     vtr_wait<ND>(alo, ahi); VTR_SET(blo, bhi, vb, 1); PV_MMA(alo, ahi, pfb[0]);
;     vtr_wait<ND>(blo, bhi); VTR_SET(alo, ahi, vb, 2); PV_MMA(blo, bhi, pfb[1]);
;     vtr_wait<ND>(alo, ahi); VTR_SET(blo, bhi, vb, 3); PV_MMA(alo, ahi, pfb[2]);
;     vtr_wait<ND>(blo, bhi); PV_MMA(blo, bhi, pfb[3]);
; template <int DQK, int DV, int kpitch, int vpitch>
; DI void attn_map(LAS unsigned char* lds, const bf16x8 (&qf)[DQK / 16], const bf16* Kg, const bf16* Vg, f32x16 (&o)[DV / 32], float& lsum, int tid, int lane) {
;     ...
;     for (int s = 0; s < NSTEP; ++s) {
;         asm volatile("s_waitcnt vmcnt(0)" ::: "memory");
;         __builtin_amdgcn_s_barrier();
;         asm volatile("" ::: "memory");
;         if (s + 1 < NSTEP) ATT_DMA2((s + 1) & 1);
;         const LAS unsigned char* ta = lds + (s & 1) * 2 * TILE;
;         attn_step2<DQK, DV, KSTR, VSTR>(ta, ta + TILE, koff, voff, qf, o, l0, l1, l2, l3);
;     }
	v_mfma_f32_32x32x16_bf16 v[0:15], v[124:127], v[160:163], v[0:15]
	ds_read_b64_tr_b16 v[124:125], v201 offset:15552
	ds_read_b64_tr_b16 v[126:127], v201 offset:18112
	v_exp_f32_e32 v69, v69
	v_exp_f32_e32 v70, v70
	v_exp_f32_e32 v71, v71
	s_waitcnt lgkmcnt(6)
	v_mfma_f32_32x32x16_bf16 v[48:63], v[112:115], v[164:167], v[48:63]
	ds_read_b64_tr_b16 v[112:113], v201 offset:32768
	ds_read_b64_tr_b16 v[114:115], v201 offset:35328
	v_exp_f32_e32 v72, v72
	v_exp_f32_e32 v73, v73
	v_exp_f32_e32 v74, v74
	s_waitcnt lgkmcnt(6)
	v_mfma_f32_32x32x16_bf16 v[32:47], v[116:119], v[164:167], v[32:47]
	ds_read_b64_tr_b16 v[116:117], v201 offset:32832
	ds_read_b64_tr_b16 v[118:119], v201 offset:35392
	v_exp_f32_e32 v75, v75
	v_exp_f32_e32 v76, v76
	v_exp_f32_e32 v77, v77
	s_waitcnt lgkmcnt(6)
	v_mfma_f32_32x32x16_bf16 v[16:31], v[120:123], v[164:167], v[16:31]
	ds_read_b64_tr_b16 v[120:121], v201 offset:32896
	ds_read_b64_tr_b16 v[122:123], v201 offset:35456
	v_exp_f32_e32 v78, v78
	v_exp_f32_e32 v79, v79
	v_cvt_pk_bf16_f32 v160, v64, v65
	s_waitcnt lgkmcnt(6)
	v_mfma_f32_32x32x16_bf16 v[0:15], v[124:127], v[164:167], v[0:15]
	ds_read_b64_tr_b16 v[124:125], v201 offset:32960
	ds_read_b64_tr_b16 v[126:127], v201 offset:35520
	v_cvt_pk_bf16_f32 v161, v66, v67
	v_cvt_pk_bf16_f32 v162, v68, v69
	v_cvt_pk_bf16_f32 v163, v70, v71
	v_cvt_pk_bf16_f32 v164, v72, v73
	v_cvt_pk_bf16_f32 v165, v74, v75
	s_waitcnt lgkmcnt(6)
	v_mfma_f32_32x32x16_bf16 v[48:63], v[112:115], v[152:155], v[48:63]
	ds_read_b64_tr_b16 v[112:113], v201 offset:37888
	ds_read_b64_tr_b16 v[114:115], v201 offset:40448
	v_cvt_pk_bf16_f32 v166, v76, v77
	v_cvt_pk_bf16_f32 v167, v78, v79
	v_add_f32_e32 v168, v168, v80
	v_add_f32_e32 v169, v169, v81
	v_add_f32_e32 v170, v170, v82
	s_waitcnt lgkmcnt(6)
	v_mfma_f32_32x32x16_bf16 v[32:47], v[116:119], v[152:155], v[32:47]
	ds_read_b64_tr_b16 v[116:117], v201 offset:37952
	ds_read_b64_tr_b16 v[118:119], v201 offset:40512
	v_add_f32_e32 v171, v171, v83
	v_add_f32_e32 v168, v168, v84
	v_add_f32_e32 v169, v169, v85
	v_add_f32_e32 v170, v170, v86
	v_add_f32_e32 v171, v171, v87
	s_waitcnt lgkmcnt(6)
	v_mfma_f32_32x32x16_bf16 v[16:31], v[120:123], v[152:155], v[16:31]
	ds_read_b64_tr_b16 v[120:121], v201 offset:38016
	ds_read_b64_tr_b16 v[122:123], v201 offset:40576
	v_add_f32_e32 v168, v168, v88
	v_add_f32_e32 v169, v169, v89
	v_add_f32_e32 v170, v170, v90
	v_add_f32_e32 v171, v171, v91
	v_add_f32_e32 v168, v168, v92
	s_waitcnt lgkmcnt(6)
	v_mfma_f32_32x32x16_bf16 v[0:15], v[124:127], v[152:155], v[0:15]
	ds_read_b64_tr_b16 v[124:125], v201 offset:38080
	ds_read_b64_tr_b16 v[126:127], v201 offset:40640
	v_add_f32_e32 v169, v169, v93
	v_add_f32_e32 v170, v170, v94
	v_add_f32_e32 v171, v171, v95
	v_add_f32_e32 v168, v168, v96
	v_add_f32_e32 v169, v169, v97
	s_waitcnt lgkmcnt(6)
	v_mfma_f32_32x32x16_bf16 v[48:63], v[112:115], v[156:159], v[48:63]
	ds_read_b64_tr_b16 v[112:113], v201 offset:43008
	ds_read_b64_tr_b16 v[114:115], v201 offset:45568
	v_add_f32_e32 v170, v170, v98
	v_add_f32_e32 v171, v171, v99
	v_add_f32_e32 v168, v168, v100
	v_add_f32_e32 v169, v169, v101
	v_add_f32_e32 v170, v170, v102
	s_waitcnt lgkmcnt(6)
	v_mfma_f32_32x32x16_bf16 v[32:47], v[116:119], v[156:159], v[32:47]
	ds_read_b64_tr_b16 v[116:117], v201 offset:43072
	ds_read_b64_tr_b16 v[118:119], v201 offset:45632
	v_add_f32_e32 v171, v171, v103
	v_add_f32_e32 v168, v168, v104
	v_add_f32_e32 v169, v169, v105
	v_add_f32_e32 v170, v170, v106
	v_add_f32_e32 v171, v171, v107
	s_waitcnt lgkmcnt(6)
	v_mfma_f32_32x32x16_bf16 v[16:31], v[120:123], v[156:159], v[16:31]
	ds_read_b64_tr_b16 v[120:121], v201 offset:43136
	ds_read_b64_tr_b16 v[122:123], v201 offset:45696
	v_add_f32_e32 v168, v168, v108
	v_add_f32_e32 v169, v169, v109
	v_add_f32_e32 v170, v170, v110
	v_add_f32_e32 v171, v171, v111
	v_add_f32_e32 v168, v168, v64
	s_waitcnt lgkmcnt(6)
	v_mfma_f32_32x32x16_bf16 v[0:15], v[124:127], v[156:159], v[0:15]
	ds_read_b64_tr_b16 v[124:125], v201 offset:43200
	ds_read_b64_tr_b16 v[126:127], v201 offset:45760
	v_add_f32_e32 v169, v169, v65
	v_add_f32_e32 v170, v170, v66
	v_add_f32_e32 v171, v171, v67
	v_add_f32_e32 v168, v168, v68
	v_add_f32_e32 v169, v169, v69
	s_waitcnt lgkmcnt(6)
	v_mfma_f32_32x32x16_bf16 v[48:63], v[112:115], v[160:163], v[48:63]
	ds_read_b64_tr_b16 v[112:113], v201 offset:48128
	ds_read_b64_tr_b16 v[114:115], v201 offset:50688
	v_add_f32_e32 v170, v170, v70
	v_add_f32_e32 v171, v171, v71
	v_add_f32_e32 v168, v168, v72
	v_add_f32_e32 v169, v169, v73
	v_add_f32_e32 v170, v170, v74
	s_waitcnt lgkmcnt(6)
	v_mfma_f32_32x32x16_bf16 v[32:47], v[116:119], v[160:163], v[32:47]
	ds_read_b64_tr_b16 v[116:117], v201 offset:48192
	ds_read_b64_tr_b16 v[118:119], v201 offset:50752
	v_add_f32_e32 v171, v171, v75
	v_add_f32_e32 v168, v168, v76
	v_add_f32_e32 v169, v169, v77
	v_add_f32_e32 v170, v170, v78
	v_add_f32_e32 v171, v171, v79
	s_waitcnt lgkmcnt(6)
	v_mfma_f32_32x32x16_bf16 v[16:31], v[120:123], v[160:163], v[16:31]
	ds_read_b64_tr_b16 v[120:121], v201 offset:48256
	ds_read_b64_tr_b16 v[122:123], v201 offset:50816
	s_waitcnt lgkmcnt(6)
	v_mfma_f32_32x32x16_bf16 v[0:15], v[124:127], v[160:163], v[0:15]
	ds_read_b64_tr_b16 v[124:125], v201 offset:48320
	ds_read_b64_tr_b16 v[126:127], v201 offset:50880
	s_waitcnt lgkmcnt(6)
	v_mfma_f32_32x32x16_bf16 v[48:63], v[112:115], v[164:167], v[48:63]
	s_waitcnt lgkmcnt(4)
	v_mfma_f32_32x32x16_bf16 v[32:47], v[116:119], v[164:167], v[32:47]
	s_waitcnt lgkmcnt(2)
	v_mfma_f32_32x32x16_bf16 v[16:31], v[120:123], v[164:167], v[16:31]
	s_waitcnt lgkmcnt(0)
	v_mfma_f32_32x32x16_bf16 v[0:15], v[124:127], v[164:167], v[0:15]
	s_cmp_lg_u32 s25, 0x100000
	s_mov_b32 s26, s25
	s_cbranch_scc0 .LBB0_1845
.LBB0_1825:
	s_waitcnt vmcnt(0)
	s_barrier
	s_add_i32 s25, s26, 0x10000
	s_branch .LBB0_1824

; #define LAS __attribute__((address_space(3)))
; #define MFMA32(a, b, c) __builtin_amdgcn_mfma_f32_32x32x16_bf16((a), (b), (c), 0, 0, 0)
; #define ATT_DMA2(ss) do { _Pragma("unroll") for (int hf = 0; hf < 2; ++hf) _Pragma("unroll") for (int j = 0; j < 4; ++j) if ((j * 8 + wave) * 64 < NKCH + NVCH) { \
;         __builtin_amdgcn_global_load_lds((const unsigned*)src[j], (LAS unsigned*)(lds + ((ss) * 2 + hf) * TILE + (j * 8 + wave) * 1024), 16, 0, 0); src[j] += step[j]; } } while (0)
; template <int DQK, int DV, int KSTR, int VSTR>
; DI void attn_step2(const LAS unsigned char* ta, const LAS unsigned char* tb, int koff, int voff, const bf16x8 (&qf)[DQK / 16], f32x16 (&o)[DV / 32], float& l0, float& l1, float& l2, float& l3) {
;     ...
;     for (int ks = 0; ks < NKS; ++ks) {
;         const bf16x8 k0 = *(const LAS bf16x8*)(ta + koff + ks * 32), k1 = *(const LAS bf16x8*)(ta + koff + 32 * KSTR + ks * 32);
;         sa[0] = MFMA32(k0, qf[ks], ks == 0 ? zero16 : sa[0]); sa[1] = MFMA32(k1, qf[ks], ks == 0 ? zero16 : sa[1]);
; template <int DQK, int DV, int kpitch, int vpitch>
; DI void attn_map(LAS unsigned char* lds, const bf16x8 (&qf)[DQK / 16], const bf16* Kg, const bf16* Vg, f32x16 (&o)[DV / 32], float& lsum, int tid, int lane) {
;     ...
;     const int r = lane & 31, h = lane >> 5;
;     const int koff = r * KSTR + h * 16;
;     const int voff = KBUF + (4 * h + ((lane & 15) >> 2)) * VSTR + (((lane >> 4) & 1) * 16 + (lane & 3) * 4) * 2;
;     float l0 = 0.f, l1 = 0.f, l2 = 0.f, l3 = 0.f;
; #pragma unroll
;     for (int d = 0; d < DV / 32; ++d)
; #pragma unroll
;         for (int i = 0; i < 16; ++i) o[d][i] = 0.f;
;     asm volatile("" ::: "memory");
;     __builtin_amdgcn_s_barrier();
;     asm volatile("" ::: "memory");
;     ATT_DMA2(0);
.LBB0_1887:
	v_mov_b32_e32 v169, 0
	s_lshl_b32 s22, s22, 10
	s_lshl_b32 s23, s23, 10
	s_lshl_b32 s24, s24, 10
	s_mov_b32 s26, 0
	v_mov_b32_e32 v171, 0
	v_mov_b32_e32 v168, 0
	v_mov_b32_e32 v170, 0
	v_mov_b32_e32 v16, 0
	v_mov_b32_e32 v17, v169
	v_mov_b32_e32 v18, v169
	v_mov_b32_e32 v19, v169
	v_mov_b32_e32 v20, v169
	v_mov_b32_e32 v21, v169
	v_mov_b32_e32 v22, v169
	v_mov_b32_e32 v23, v169
	v_mov_b32_e32 v24, v169
	v_mov_b32_e32 v25, v169
	v_mov_b32_e32 v26, v169
	v_mov_b32_e32 v27, v169
	v_mov_b32_e32 v28, v169
	v_mov_b32_e32 v29, v169
	v_mov_b32_e32 v30, v169
	v_mov_b32_e32 v31, v169
	v_mov_b32_e32 v32, 0
	v_mov_b32_e32 v33, v169
	v_mov_b32_e32 v34, v169
	v_mov_b32_e32 v35, v169
	v_mov_b32_e32 v36, v169
	v_mov_b32_e32 v37, v169
	v_mov_b32_e32 v38, v169
	v_mov_b32_e32 v39, v169
	v_mov_b32_e32 v40, v169
	v_mov_b32_e32 v41, v169
	v_mov_b32_e32 v42, v169
	v_mov_b32_e32 v43, v169
	v_mov_b32_e32 v44, v169
	v_mov_b32_e32 v45, v169
	v_mov_b32_e32 v46, v169
	v_mov_b32_e32 v47, v169
	v_mov_b32_e32 v48, 0
	v_mov_b32_e32 v49, v169
	v_mov_b32_e32 v50, v169
	v_mov_b32_e32 v51, v169
	v_mov_b32_e32 v52, v169
	v_mov_b32_e32 v53, v169
	v_mov_b32_e32 v54, v169
	v_mov_b32_e32 v55, v169
	v_mov_b32_e32 v56, v169
	v_mov_b32_e32 v57, v169
	v_mov_b32_e32 v58, v169
	v_mov_b32_e32 v59, v169
	v_mov_b32_e32 v60, v169
	v_mov_b32_e32 v61, v169
	v_mov_b32_e32 v62, v169
	v_mov_b32_e32 v63, v169
	v_mov_b32_e32 v0, 0
	v_mov_b32_e32 v1, v169
	v_mov_b32_e32 v2, v169
	v_mov_b32_e32 v3, v169
	v_mov_b32_e32 v4, v169
	v_mov_b32_e32 v5, v169
	v_mov_b32_e32 v6, v169
	v_mov_b32_e32 v7, v169
	v_mov_b32_e32 v8, v169
	v_mov_b32_e32 v9, v169
	v_mov_b32_e32 v10, v169
	v_mov_b32_e32 v11, v169
	v_mov_b32_e32 v12, v169
	v_mov_b32_e32 v13, v169
	v_mov_b32_e32 v14, v169
	v_mov_b32_e32 v15, v169
	s_waitcnt vmcnt(0)
	v_readfirstlane_b32 s86, v64
	v_readfirstlane_b32 s87, v65
	s_nop 0
	s_sub_u32 s86, s86, 0x100
	s_subb_u32 s87, s87, 0
	v_subrev_u32_e32 v128, s86, v64
	v_subrev_u32_e32 v130, s86, v66
	v_subrev_u32_e32 v132, s86, v68
	v_subrev_u32_e32 v134, s86, v70
	s_branch .LBB0_1889
.LBB0_1888:
	s_and_b32 s10, s26, 0x10000
	v_add_u32_e32 v176, s10, v197
	v_add_u32_e32 v202, s10, v209
	v_add_u32_e32 v202, 0x2400, v202
	s_and_b32 s27, s25, 0x10000
	s_cmp_eq_u32 s26, 0xf0000
	s_cselect_b64 s[44:45], -1, 0
	ds_read_b128 v[212:215], v176
	ds_read_b128 v[216:219], v176 offset:32
	ds_read_b128 v[220:223], v176 offset:64
	ds_read_b128 v[224:227], v176 offset:96
	ds_read_b128 v[172:175], v176 offset:4608
	ds_read_b128 v[178:181], v176 offset:4640
	s_waitcnt lgkmcnt(5)
	v_mfma_f32_32x32x16_bf16 v[64:79], v[212:215], v[136:139], 0
	ds_read_b128 v[212:215], v176 offset:4672
	s_or_b64 s[10:11], s[44:45], s[0:1]
	s_cbranch_scc1 .Ldiff2_dma_skip_0
	s_add_i32 m0, s27, s22
	s_nop 0
	global_load_lds_dwordx4 v128, s[86:87]

; #define LAS __attribute__((address_space(3)))
; #define MFMA32(a, b, c) __builtin_amdgcn_mfma_f32_32x32x16_bf16((a), (b), (c), 0, 0, 0)
; #define VTR_SET(lo, hi, c) do { _Pragma("unroll") for (int d = 0; d < ND; ++d) { \
;         VTR_ASM(lo[d], va, (32 * ((c) >> 1) + 16 * ((c) & 1)) * VSTR + d * 64); VTR_ASM(hi[d], va, (32 * ((c) >> 1) + 16 * ((c) & 1)) * VSTR + d * 64 + 8 * VSTR); } } while (0)
; #define PV_MMA(lo, hi, c) do { _Pragma("unroll") for (int d = 0; d < ND; ++d) { const bf16x8 vf = __builtin_shufflevector(lo[d], hi[d], 0, 1, 2, 3, 4, 5, 6, 7); o[d] = MFMA32(vf, pf[(c) >> 1][(c) & 1], o[d]); } } while (0)
; #define VTR_SET(lo, hi, base, c) do { _Pragma("unroll") for (int d = 0; d < ND; ++d) { \
;         VTR_ASM(lo[d], base, (32 * ((c) >> 1) + 16 * ((c) & 1)) * VSTR + d * 64); VTR_ASM(hi[d], base, (32 * ((c) >> 1) + 16 * ((c) & 1)) * VSTR + d * 64 + 8 * VSTR); } } while (0)
; #define PV_MMA(lo, hi, pf_) do { _Pragma("unroll") for (int d = 0; d < ND; ++d) { const bf16x8 vf = __builtin_shufflevector(lo[d], hi[d], 0, 1, 2, 3, 4, 5, 6, 7); o[d] = MFMA32(vf, pf_, o[d]); } } while (0)
; template <int DQK, int DV, int KSTR, int VSTR>
; DI void attn_step2(const LAS unsigned char* ta, const LAS unsigned char* tb, int koff, int voff, const bf16x8 (&qf)[DQK / 16], f32x16 (&o)[DV / 32], float& l0, float& l1, float& l2, float& l3) {
;     ...
;     for (int c = 0; c < 4; ++c) {
; #pragma unroll
;         for (int ks = (c * NKS) / 4; ks < ((c + 1) * NKS) / 4; ++ks) {
;             const bf16x8 k0 = *(const LAS bf16x8*)(tb + koff + ks * 32), k1 = *(const LAS bf16x8*)(tb + koff + 32 * KSTR + ks * 32);
;             sb[0] = MFMA32(k0, qf[ks], ks == 0 ? zero16 : sb[0]); sb[1] = MFMA32(k1, qf[ks], ks == 0 ? zero16 : sb[1]);
;         }
;         SM_CHUNK(sa, pfa[c], c);
;     }
;     vtr_wait<ND>(alo, ahi); VTR_SET(blo, bhi, va, 1); PV_MMA(alo, ahi, pfa[0]); SM_CHUNK(sb, pfb[0], 0);
;     vtr_wait<ND>(blo, bhi); VTR_SET(alo, ahi, va, 2); PV_MMA(blo, bhi, pfa[1]); SM_CHUNK(sb, pfb[1], 1);
;     vtr_wait<ND>(alo, ahi); VTR_SET(blo, bhi, va, 3); PV_MMA(alo, ahi, pfa[2]); SM_CHUNK(sb, pfb[2], 2);
;     vtr_wait<ND>(blo, bhi); VTR_SET(alo, ahi, vb, 0); PV_MMA(blo, bhi, pfa[3]); SM_CHUNK(sb, pfb[3], 3);
.Ldiff2_dma_skip_6:
	v_exp_f32_e32 v67, v67
	v_exp_f32_e32 v68, v68
	v_exp_f32_e32 v69, v69
	s_waitcnt lgkmcnt(5)
	v_mfma_f32_32x32x16_bf16 v[80:95], v[216:219], v[148:151], v[80:95]
	ds_read_b128 v[216:219], v176 offset:37408
	ds_read_b64_tr_b16 v[112:113], v202
	ds_read_b64_tr_b16 v[114:115], v202 offset:2560
	s_orn2_b64 s[10:11], s[44:45], s[68:69]
	s_cbranch_scc1 .Ldiff2_dma_skip_7
	s_add_i32 s10, s27, s13
	s_add_i32 m0, s10, 0x8000
	s_nop 0
	global_load_lds_dwordx4 v134, s[86:87]
.Ldiff2_dma_skip_7:
	s_add_u32 s86, s86, s82
	s_addc_u32 s87, s87, s83
	v_exp_f32_e32 v70, v70
	v_exp_f32_e32 v71, v71
	v_exp_f32_e32 v72, v72
	s_waitcnt lgkmcnt(7)
	v_mfma_f32_32x32x16_bf16 v[96:111], v[220:223], v[136:139], 0
	ds_read_b128 v[220:223], v176 offset:37440
	ds_read_b64_tr_b16 v[116:117], v202 offset:64
	ds_read_b64_tr_b16 v[118:119], v202 offset:2624
	v_exp_f32_e32 v73, v73
	v_exp_f32_e32 v74, v74
	v_exp_f32_e32 v75, v75
	s_waitcnt lgkmcnt(9)
	v_mfma_f32_32x32x16_bf16 v[96:111], v[224:227], v[140:143], v[96:111]
	ds_read_b128 v[224:227], v176 offset:37472
	ds_read_b64_tr_b16 v[120:121], v202 offset:128
	ds_read_b64_tr_b16 v[122:123], v202 offset:2688
	v_exp_f32_e32 v76, v76
	v_exp_f32_e32 v77, v77
	v_exp_f32_e32 v78, v78
	s_waitcnt lgkmcnt(11)
	v_mfma_f32_32x32x16_bf16 v[96:111], v[172:175], v[144:147], v[96:111]
	ds_read_b64_tr_b16 v[124:125], v202 offset:192
	ds_read_b64_tr_b16 v[126:127], v202 offset:2752
	v_exp_f32_e32 v79, v79
	v_cvt_pk_bf16_f32 v152, v64, v65
	v_cvt_pk_bf16_f32 v153, v66, v67
	v_cvt_pk_bf16_f32 v154, v68, v69
	v_cvt_pk_bf16_f32 v155, v70, v71
	s_waitcnt lgkmcnt(12)
	v_mfma_f32_32x32x16_bf16 v[96:111], v[178:181], v[148:151], v[96:111]
	v_cvt_pk_bf16_f32 v156, v72, v73
	v_cvt_pk_bf16_f32 v157, v74, v75
	v_cvt_pk_bf16_f32 v158, v76, v77
	v_cvt_pk_bf16_f32 v159, v78, v79
	v_exp_f32_e32 v80, v80
	s_waitcnt lgkmcnt(8)
	v_mfma_f32_32x32x16_bf16 v[0:15], v[112:115], v[152:155], v[0:15]
	ds_read_b64_tr_b16 v[112:113], v202 offset:5120
	ds_read_b64_tr_b16 v[114:115], v202 offset:7680
	v_exp_f32_e32 v81, v81
	v_exp_f32_e32 v82, v82
	v_exp_f32_e32 v83, v83
	s_waitcnt lgkmcnt(7)
	v_mfma_f32_32x32x16_bf16 v[48:63], v[116:119], v[152:155], v[48:63]
	ds_read_b64_tr_b16 v[116:117], v202 offset:5184
	ds_read_b64_tr_b16 v[118:119], v202 offset:7744
	v_exp_f32_e32 v84, v84
	v_exp_f32_e32 v85, v85
	v_exp_f32_e32 v86, v86
	s_waitcnt lgkmcnt(6)
	v_mfma_f32_32x32x16_bf16 v[32:47], v[120:123], v[152:155], v[32:47]
	ds_read_b64_tr_b16 v[120:121], v202 offset:5248
	ds_read_b64_tr_b16 v[122:123], v202 offset:7808
	v_exp_f32_e32 v87, v87
	v_exp_f32_e32 v88, v88
	v_exp_f32_e32 v89, v89
	s_waitcnt lgkmcnt(6)
	v_mfma_f32_32x32x16_bf16 v[16:31], v[124:127], v[152:155], v[16:31]
	ds_read_b64_tr_b16 v[124:125], v202 offset:5312
	ds_read_b64_tr_b16 v[126:127], v202 offset:7872
	v_exp_f32_e32 v90, v90
	v_exp_f32_e32 v91, v91
	v_exp_f32_e32 v92, v92
	s_waitcnt lgkmcnt(6)
	v_mfma_f32_32x32x16_bf16 v[0:15], v[112:115], v[156:159], v[0:15]
	ds_read_b64_tr_b16 v[112:113], v202 offset:10240
	ds_read_b64_tr_b16 v[114:115], v202 offset:12800
	v_exp_f32_e32 v93, v93
	v_exp_f32_e32 v94, v94
	v_exp_f32_e32 v95, v95
	s_waitcnt lgkmcnt(6)
	v_mfma_f32_32x32x16_bf16 v[48:63], v[116:119], v[156:159], v[48:63]
	ds_read_b64_tr_b16 v[116:117], v202 offset:10304
	ds_read_b64_tr_b16 v[118:119], v202 offset:12864
	v_cvt_pk_bf16_f32 v160, v80, v81
	v_cvt_pk_bf16_f32 v161, v82, v83
	v_cvt_pk_bf16_f32 v162, v84, v85
	v_cvt_pk_bf16_f32 v163, v86, v87
	v_cvt_pk_bf16_f32 v164, v88, v89
	v_cvt_pk_bf16_f32 v165, v90, v91
	s_waitcnt lgkmcnt(6)
	v_mfma_f32_32x32x16_bf16 v[32:47], v[120:123], v[156:159], v[32:47]
	ds_read_b64_tr_b16 v[120:121], v202 offset:10368
	ds_read_b64_tr_b16 v[122:123], v202 offset:12928
	v_cvt_pk_bf16_f32 v166, v92, v93
	v_cvt_pk_bf16_f32 v167, v94, v95
	v_exp_f32_e32 v96, v96
	v_exp_f32_e32 v97, v97
	s_waitcnt lgkmcnt(6)
	v_mfma_f32_32x32x16_bf16 v[16:31], v[124:127], v[156:159], v[16:31]
	ds_read_b64_tr_b16 v[124:125], v202 offset:10432
	ds_read_b64_tr_b16 v[126:127], v202 offset:12992
	v_exp_f32_e32 v98, v98
	v_exp_f32_e32 v99, v99
	v_exp_f32_e32 v100, v100
	v_add_f32_e32 v168, v168, v64
	v_add_f32_e32 v169, v169, v65
	v_add_f32_e32 v170, v170, v66
	v_add_f32_e32 v171, v171, v67
	v_add_f32_e32 v168, v168, v68
	v_add_f32_e32 v169, v169, v69
	v_add_f32_e32 v170, v170, v70
	v_add_f32_e32 v171, v171, v71
	v_add_f32_e32 v168, v168, v72
	v_add_f32_e32 v169, v169, v73
	v_add_f32_e32 v170, v170, v74
	v_add_f32_e32 v171, v171, v75
	v_add_f32_e32 v168, v168, v76
	v_add_f32_e32 v169, v169, v77
	v_add_f32_e32 v170, v170, v78
	v_add_f32_e32 v171, v171, v79
	v_mfma_f32_32x32x16_bf16 v[64:79], v[212:215], v[136:139], 0
	v_exp_f32_e32 v101, v101
	v_exp_f32_e32 v102, v102
	v_exp_f32_e32 v103, v103
	v_mfma_f32_32x32x16_bf16 v[64:79], v[216:219], v[140:143], v[64:79]
	v_exp_f32_e32 v104, v104
	v_exp_f32_e32 v105, v105
	v_exp_f32_e32 v106, v106
	v_mfma_f32_32x32x16_bf16 v[64:79], v[220:223], v[144:147], v[64:79]
	v_exp_f32_e32 v107, v107
	v_exp_f32_e32 v108, v108
	v_exp_f32_e32 v109, v109
	v_mfma_f32_32x32x16_bf16 v[64:79], v[224:227], v[148:151], v[64:79]
	v_exp_f32_e32 v110, v110
	v_exp_f32_e32 v111, v111
	v_cvt_pk_bf16_f32 v152, v96, v97
	s_waitcnt lgkmcnt(6)
	v_mfma_f32_32x32x16_bf16 v[0:15], v[112:115], v[160:163], v[0:15]
	ds_read_b64_tr_b16 v[112:113], v202 offset:15360
	ds_read_b64_tr_b16 v[114:115], v202 offset:17920
	v_cvt_pk_bf16_f32 v153, v98, v99
	v_cvt_pk_bf16_f32 v154, v100, v101
	v_cvt_pk_bf16_f32 v155, v102, v103
	v_cvt_pk_bf16_f32 v156, v104, v105
	v_cvt_pk_bf16_f32 v157, v106, v107
	s_waitcnt lgkmcnt(6)
; #define LAS __attribute__((address_space(3)))
; #define VTR_SET(lo, hi, c) do { _Pragma("unroll") for (int d = 0; d < ND; ++d) { \
;         VTR_ASM(lo[d], va, (32 * ((c) >> 1) + 16 * ((c) & 1)) * VSTR + d * 64); VTR_ASM(hi[d], va, (32 * ((c) >> 1) + 16 * ((c) & 1)) * VSTR + d * 64 + 8 * VSTR); } } while (0)
; #define PV_MMA(lo, hi, c) do { _Pragma("unroll") for (int d = 0; d < ND; ++d) { const bf16x8 vf = __builtin_shufflevector(lo[d], hi[d], 0, 1, 2, 3, 4, 5, 6, 7); o[d] = MFMA32(vf, pf[(c) >> 1][(c) & 1], o[d]); } } while (0)
; #define VTR_SET(lo, hi, base, c) do { _Pragma("unroll") for (int d = 0; d < ND; ++d) { \
;         VTR_ASM(lo[d], base, (32 * ((c) >> 1) + 16 * ((c) & 1)) * VSTR + d * 64); VTR_ASM(hi[d], base, (32 * ((c) >> 1) + 16 * ((c) & 1)) * VSTR + d * 64 + 8 * VSTR); } } while (0)
; #define PV_MMA(lo, hi, pf_) do { _Pragma("unroll") for (int d = 0; d < ND; ++d) { const bf16x8 vf = __builtin_shufflevector(lo[d], hi[d], 0, 1, 2, 3, 4, 5, 6, 7); o[d] = MFMA32(vf, pf_, o[d]); } } while (0)
; template <int DQK, int DV, int KSTR, int VSTR>
; DI void attn_step2(const LAS unsigned char* ta, const LAS unsigned char* tb, int koff, int voff, const bf16x8 (&qf)[DQK / 16], f32x16 (&o)[DV / 32], float& l0, float& l1, float& l2, float& l3) {
;     ...
;     vtr_wait<ND>(alo, ahi); VTR_SET(blo, bhi, va, 3); PV_MMA(alo, ahi, pfa[2]); SM_CHUNK(sb, pfb[2], 2);
;     vtr_wait<ND>(blo, bhi); VTR_SET(alo, ahi, vb, 0); PV_MMA(blo, bhi, pfa[3]); SM_CHUNK(sb, pfb[3], 3);
;     vtr_wait<ND>(alo, ahi); VTR_SET(blo, bhi, vb, 1); PV_MMA(alo, ahi, pfb[0]);
;     vtr_wait<ND>(blo, bhi); VTR_SET(alo, ahi, vb, 2); PV_MMA(blo, bhi, pfb[1]);
;     vtr_wait<ND>(alo, ahi); VTR_SET(blo, bhi, vb, 3); PV_MMA(alo, ahi, pfb[2]);
;     vtr_wait<ND>(blo, bhi); PV_MMA(blo, bhi, pfb[3]);
; template <int DQK, int DV, int kpitch, int vpitch>
; DI void attn_map(LAS unsigned char* lds, const bf16x8 (&qf)[DQK / 16], const bf16* Kg, const bf16* Vg, f32x16 (&o)[DV / 32], float& lsum, int tid, int lane) {
;     ...
;     for (int s = 0; s < NSTEP; ++s) {
;         asm volatile("s_waitcnt vmcnt(0)" ::: "memory");
;         __builtin_amdgcn_s_barrier();
;         asm volatile("" ::: "memory");
;         if (s + 1 < NSTEP) ATT_DMA2((s + 1) & 1);
;         const LAS unsigned char* ta = lds + (s & 1) * 2 * TILE;
;         attn_step2<DQK, DV, KSTR, VSTR>(ta, ta + TILE, koff, voff, qf, o, l0, l1, l2, l3);
;     }
	v_mfma_f32_32x32x16_bf16 v[48:63], v[116:119], v[160:163], v[48:63]
	ds_read_b64_tr_b16 v[116:117], v202 offset:15424
	ds_read_b64_tr_b16 v[118:119], v202 offset:17984
	v_cvt_pk_bf16_f32 v158, v108, v109
	v_cvt_pk_bf16_f32 v159, v110, v111
	v_exp_f32_e32 v64, v64
	v_exp_f32_e32 v65, v65
	s_waitcnt lgkmcnt(6)
	v_mfma_f32_32x32x16_bf16 v[32:47], v[120:123], v[160:163], v[32:47]
	ds_read_b64_tr_b16 v[120:121], v202 offset:15488
	ds_read_b64_tr_b16 v[122:123], v202 offset:18048
	v_exp_f32_e32 v66, v66
	v_exp_f32_e32 v67, v67
	v_exp_f32_e32 v68, v68
	s_waitcnt lgkmcnt(6)
	v_mfma_f32_32x32x16_bf16 v[16:31], v[124:127], v[160:163], v[16:31]
	ds_read_b64_tr_b16 v[124:125], v202 offset:15552
	ds_read_b64_tr_b16 v[126:127], v202 offset:18112
	v_exp_f32_e32 v69, v69
	v_exp_f32_e32 v70, v70
	v_exp_f32_e32 v71, v71
	s_waitcnt lgkmcnt(6)
	v_mfma_f32_32x32x16_bf16 v[0:15], v[112:115], v[164:167], v[0:15]
	ds_read_b64_tr_b16 v[112:113], v202 offset:32768
	ds_read_b64_tr_b16 v[114:115], v202 offset:35328
	v_exp_f32_e32 v72, v72
	v_exp_f32_e32 v73, v73
	v_exp_f32_e32 v74, v74
	s_waitcnt lgkmcnt(6)
	v_mfma_f32_32x32x16_bf16 v[48:63], v[116:119], v[164:167], v[48:63]
	ds_read_b64_tr_b16 v[116:117], v202 offset:32832
	ds_read_b64_tr_b16 v[118:119], v202 offset:35392
	v_exp_f32_e32 v75, v75
	v_exp_f32_e32 v76, v76
	v_exp_f32_e32 v77, v77
	s_waitcnt lgkmcnt(6)
	v_mfma_f32_32x32x16_bf16 v[32:47], v[120:123], v[164:167], v[32:47]
	ds_read_b64_tr_b16 v[120:121], v202 offset:32896
	ds_read_b64_tr_b16 v[122:123], v202 offset:35456
	v_exp_f32_e32 v78, v78
	v_exp_f32_e32 v79, v79
	v_cvt_pk_bf16_f32 v160, v64, v65
	s_waitcnt lgkmcnt(6)
	v_mfma_f32_32x32x16_bf16 v[16:31], v[124:127], v[164:167], v[16:31]
	ds_read_b64_tr_b16 v[124:125], v202 offset:32960
	ds_read_b64_tr_b16 v[126:127], v202 offset:35520
	v_cvt_pk_bf16_f32 v161, v66, v67
	v_cvt_pk_bf16_f32 v162, v68, v69
	v_cvt_pk_bf16_f32 v163, v70, v71
	v_cvt_pk_bf16_f32 v164, v72, v73
	v_cvt_pk_bf16_f32 v165, v74, v75
	s_waitcnt lgkmcnt(6)
	v_mfma_f32_32x32x16_bf16 v[0:15], v[112:115], v[152:155], v[0:15]
	ds_read_b64_tr_b16 v[112:113], v202 offset:37888
	ds_read_b64_tr_b16 v[114:115], v202 offset:40448
	v_cvt_pk_bf16_f32 v166, v76, v77
	v_cvt_pk_bf16_f32 v167, v78, v79
	v_add_f32_e32 v168, v168, v80
	v_add_f32_e32 v169, v169, v81
	v_add_f32_e32 v170, v170, v82
	s_waitcnt lgkmcnt(6)
	v_mfma_f32_32x32x16_bf16 v[48:63], v[116:119], v[152:155], v[48:63]
	ds_read_b64_tr_b16 v[116:117], v202 offset:37952
	ds_read_b64_tr_b16 v[118:119], v202 offset:40512
	v_add_f32_e32 v171, v171, v83
	v_add_f32_e32 v168, v168, v84
	v_add_f32_e32 v169, v169, v85
	v_add_f32_e32 v170, v170, v86
	v_add_f32_e32 v171, v171, v87
	s_waitcnt lgkmcnt(6)
	v_mfma_f32_32x32x16_bf16 v[32:47], v[120:123], v[152:155], v[32:47]
	ds_read_b64_tr_b16 v[120:121], v202 offset:38016
	ds_read_b64_tr_b16 v[122:123], v202 offset:40576
	v_add_f32_e32 v168, v168, v88
	v_add_f32_e32 v169, v169, v89
	v_add_f32_e32 v170, v170, v90
	v_add_f32_e32 v171, v171, v91
	v_add_f32_e32 v168, v168, v92
	s_waitcnt lgkmcnt(6)
	v_mfma_f32_32x32x16_bf16 v[16:31], v[124:127], v[152:155], v[16:31]
	ds_read_b64_tr_b16 v[124:125], v202 offset:38080
	ds_read_b64_tr_b16 v[126:127], v202 offset:40640
	v_add_f32_e32 v169, v169, v93
	v_add_f32_e32 v170, v170, v94
	v_add_f32_e32 v171, v171, v95
	v_add_f32_e32 v168, v168, v96
	v_add_f32_e32 v169, v169, v97
	s_waitcnt lgkmcnt(6)
	v_mfma_f32_32x32x16_bf16 v[0:15], v[112:115], v[156:159], v[0:15]
	ds_read_b64_tr_b16 v[112:113], v202 offset:43008
	ds_read_b64_tr_b16 v[114:115], v202 offset:45568
	v_add_f32_e32 v170, v170, v98
	v_add_f32_e32 v171, v171, v99
	v_add_f32_e32 v168, v168, v100
	v_add_f32_e32 v169, v169, v101
	v_add_f32_e32 v170, v170, v102
	s_waitcnt lgkmcnt(6)
	v_mfma_f32_32x32x16_bf16 v[48:63], v[116:119], v[156:159], v[48:63]
	ds_read_b64_tr_b16 v[116:117], v202 offset:43072
	ds_read_b64_tr_b16 v[118:119], v202 offset:45632
	v_add_f32_e32 v171, v171, v103
	v_add_f32_e32 v168, v168, v104
	v_add_f32_e32 v169, v169, v105
	v_add_f32_e32 v170, v170, v106
	v_add_f32_e32 v171, v171, v107
	s_waitcnt lgkmcnt(6)
	v_mfma_f32_32x32x16_bf16 v[32:47], v[120:123], v[156:159], v[32:47]
	ds_read_b64_tr_b16 v[120:121], v202 offset:43136
	ds_read_b64_tr_b16 v[122:123], v202 offset:45696
	v_add_f32_e32 v168, v168, v108
	v_add_f32_e32 v169, v169, v109
	v_add_f32_e32 v170, v170, v110
	v_add_f32_e32 v171, v171, v111
	v_add_f32_e32 v168, v168, v64
	s_waitcnt lgkmcnt(6)
	v_mfma_f32_32x32x16_bf16 v[16:31], v[124:127], v[156:159], v[16:31]
	ds_read_b64_tr_b16 v[124:125], v202 offset:43200
	ds_read_b64_tr_b16 v[126:127], v202 offset:45760
	v_add_f32_e32 v169, v169, v65
	v_add_f32_e32 v170, v170, v66
	v_add_f32_e32 v171, v171, v67
	v_add_f32_e32 v168, v168, v68
	v_add_f32_e32 v169, v169, v69
	s_waitcnt lgkmcnt(6)
	v_mfma_f32_32x32x16_bf16 v[0:15], v[112:115], v[160:163], v[0:15]
	ds_read_b64_tr_b16 v[112:113], v202 offset:48128
	ds_read_b64_tr_b16 v[114:115], v202 offset:50688
	v_add_f32_e32 v170, v170, v70
	v_add_f32_e32 v171, v171, v71
	v_add_f32_e32 v168, v168, v72
	v_add_f32_e32 v169, v169, v73
	v_add_f32_e32 v170, v170, v74
	s_waitcnt lgkmcnt(6)
	v_mfma_f32_32x32x16_bf16 v[48:63], v[116:119], v[160:163], v[48:63]
	ds_read_b64_tr_b16 v[116:117], v202 offset:48192
	ds_read_b64_tr_b16 v[118:119], v202 offset:50752
	v_add_f32_e32 v171, v171, v75
	v_add_f32_e32 v168, v168, v76
	v_add_f32_e32 v169, v169, v77
	v_add_f32_e32 v170, v170, v78
	v_add_f32_e32 v171, v171, v79
	s_waitcnt lgkmcnt(6)
	v_mfma_f32_32x32x16_bf16 v[32:47], v[120:123], v[160:163], v[32:47]
	ds_read_b64_tr_b16 v[120:121], v202 offset:48256
	ds_read_b64_tr_b16 v[122:123], v202 offset:50816
	s_waitcnt lgkmcnt(6)
	v_mfma_f32_32x32x16_bf16 v[16:31], v[124:127], v[160:163], v[16:31]
	ds_read_b64_tr_b16 v[124:125], v202 offset:48320
	ds_read_b64_tr_b16 v[126:127], v202 offset:50880
	s_waitcnt lgkmcnt(6)
	v_mfma_f32_32x32x16_bf16 v[0:15], v[112:115], v[164:167], v[0:15]
	s_waitcnt lgkmcnt(4)
	v_mfma_f32_32x32x16_bf16 v[48:63], v[116:119], v[164:167], v[48:63]
	s_waitcnt lgkmcnt(2)
	v_mfma_f32_32x32x16_bf16 v[32:47], v[120:123], v[164:167], v[32:47]
	s_waitcnt lgkmcnt(0)
	v_mfma_f32_32x32x16_bf16 v[16:31], v[124:127], v[164:167], v[16:31]
	s_cmp_lg_u32 s25, 0x100000
	s_mov_b32 s26, s25
	s_cbranch_scc0 .LBB0_1780
